# SSD prep phase: dt partial / dt_bias / a_log loads of both heads issued at the top of each unit instead of in four serialized rounds
# baseline (speedup 1.0000x reference)
; DI void ssd_prep_unit(Frame& F, const Mix1Args& a, int U) {
;     ...
;     float bw[4][2], bb[2], cw[4][2], cbs[2];
; #pragma unroll
;     for (int j = 0; j < 2; ++j) { const int chb = 8192 + g * 128 + 2 * c2 + j, chc = 9216 + g * 128 + 2 * c2 + j;
;         bb[j] = a.conv_b[chb]; cbs[j] = a.conv_b[chc];
; #pragma unroll
;         for (int k = 0; k < 4; ++k) { bw[k][j] = a.conv_w[k * 10240 + chb]; cw[k][j] = a.conv_w[k * 10240 + chc]; } }
;     const long r0 = (long)b * SEQ + (long)n * 64 + 8 * rg - 3;
;     const bf16* bcol = a.proj + C_B + g * 128 + 2 * c2;
;     const bf16* ccol = a.proj + C_C + g * 128 + 2 * c2;
;     unsigned bc[11], cc[11];
; #pragma unroll
;     for (int i = 0; i < 11; ++i) { const bool zz = (n == 0 && 8 * rg - 3 + i < 0);
;         bc[i] = zz ? 0u : *(const unsigned*)(bcol + (size_t)(r0 + i) * N3P); cc[i] = zz ? 0u : *(const unsigned*)(ccol + (size_t)(r0 + i) * N3P); }
;     ...
; #pragma unroll
;     for (int t = 0; t < 2; ++t) { const int h = 16 * g + 2 * w + t;
;         const size_t di = ((size_t)b * SEQ + (size_t)n * 64 + lane) * 128 + h; const size_t dq = (size_t)16384 * 128;
;         const float xx = ((a.dtp[di] + a.dtp[di + dq]) + (a.dtp[di + 2 * dq] + a.dtp[di + 3 * dq])) + a.dt_bias[h];
;         const float dtv = xx > 20.f ? xx : log1pf(__expf(xx)); float cs = dtv * (-__expf(a.a_log[h]) * LOG2E);
; #pragma unroll
;         for (int o = 1; o < 64; o <<= 1) { const float tt = __shfl_up(cs, o); if (lane >= o) cs += tt; }
;         float* tp = a.TABg + (((size_t)(b * 128 + n)) * 128 + h) * 128; tp[lane] = cs; tp[64 + lane] = dtv; }
.LBB0_602:
	s_or_b64 exec, exec, s[14:15]
	v_mov_b32_e32 v20, v123
	s_or_b32 s16, s16, 1
	s_lshl_b64 s[14:15], s[16:17], 9
	v_lshl_add_u64 v[18:19], v[18:19], 0, s[14:15]
	global_store_dword v[18:19], v17, off offset:256
	s_add_i32 s65, s65, s92
	s_cmpk_gt_i32 s65, 0x7ff
	s_waitcnt vmcnt(1)
	v_mul_f32_e32 v20, 0x3fb8aa3b, v20
	v_exp_f32_e32 v20, v20
	s_nop 0
	v_mul_f32_e32 v20, 0xbfb8aa3b, v20
	v_mul_f32_e32 v21, v17, v20
	ds_bpermute_b32 v4, v4, v21
	s_waitcnt lgkmcnt(0)
	v_fmac_f32_e32 v4, v17, v20
	v_cndmask_b32_e64 v4, v4, v21, s[0:1]
	ds_bpermute_b32 v20, v26, v4
	s_waitcnt lgkmcnt(0)
	v_add_f32_e32 v20, v4, v20
	v_cndmask_b32_e64 v4, v20, v4, s[12:13]
	ds_bpermute_b32 v20, v28, v4
	s_waitcnt lgkmcnt(0)
	v_add_f32_e32 v20, v4, v20
	v_cndmask_b32_e64 v4, v20, v4, s[4:5]
	ds_bpermute_b32 v20, v29, v4
	s_waitcnt lgkmcnt(0)
	v_add_f32_e32 v20, v4, v20
	v_cndmask_b32_e64 v4, v20, v4, s[6:7]
	ds_bpermute_b32 v20, v30, v4
	s_waitcnt lgkmcnt(0)
	v_add_f32_e32 v20, v4, v20
	v_cndmask_b32_e64 v4, v20, v4, s[8:9]
	ds_bpermute_b32 v20, v27, v4
	s_waitcnt lgkmcnt(0)
	v_add_f32_e32 v17, v4, v20
	v_cndmask_b32_e64 v4, v17, v4, s[10:11]
	global_store_dword v[18:19], v4, off
	s_waitcnt lgkmcnt(0)
	s_barrier
	s_cbranch_scc1 .LBB0_621
.LBB0_603:
	s_and_b32 s66, s65, 7
	s_lshr_b32 s98, s65, 3
	s_lshl_b32 s98, s98, 6
	s_lshl_b32 s99, s66, 4
	v_or_b32_e32 v110, s98, v166
	s_add_i32 s99, s99, s26
	v_lshlrev_b32_e32 v110, 9, v110
	s_lshl_b32 s99, s99, 2
	s_add_u32 s100, s82, s99
	s_addc_u32 s101, s83, 0
	v_mov_b32_e32 v111, s99
	global_load_dword v112, v110, s[100:101]
	global_load_dword v116, v110, s[100:101] offset:4
	s_add_u32 s100, s100, 0x800000
	s_addc_u32 s101, s101, 0
	global_load_dword v113, v110, s[100:101]
	global_load_dword v117, v110, s[100:101] offset:4
	s_add_u32 s100, s100, 0x800000
	s_addc_u32 s101, s101, 0
	global_load_dword v114, v110, s[100:101]
	global_load_dword v118, v110, s[100:101] offset:4
	s_add_u32 s100, s100, 0x800000
	s_addc_u32 s101, s101, 0
	global_load_dword v115, v110, s[100:101]
	global_load_dword v119, v110, s[100:101] offset:4
	global_load_dword v120, v111, s[44:45]
	global_load_dword v121, v111, s[44:45] offset:4
	global_load_dword v122, v111, s[46:47]
	global_load_dword v123, v111, s[46:47] offset:4
	s_lshl_b32 s68, s66, 7
	v_or_b32_e32 v4, s68, v1
	v_lshlrev_b32_e32 v4, 2, v4
	v_lshl_add_u64 v[30:31], s[72:73], 0, v[4:5]
	v_add_co_u32_e32 v22, vcc, 0x12000, v30
	v_or_b32_e32 v17, 0x8000, v4
	s_nop 0
	v_addc_co_u32_e32 v23, vcc, 0, v31, vcc
	v_add_co_u32_e32 v24, vcc, 0x1c000, v30
	v_or_b32_e32 v34, 0x9000, v4
	s_nop 0
	v_addc_co_u32_e32 v25, vcc, 0, v31, vcc
	v_add_co_u32_e32 v32, vcc, 0x26000, v30
	global_load_dwordx2 v[18:19], v17, s[74:75]
	global_load_dwordx2 v[20:21], v17, s[72:73]
	v_addc_co_u32_e32 v33, vcc, 0, v31, vcc
	global_load_dwordx2 v[26:27], v[22:23], off
	global_load_dwordx2 v[28:29], v[24:25], off
	s_nop 0
	global_load_dwordx2 v[22:23], v34, s[74:75]
	global_load_dwordx2 v[24:25], v34, s[72:73]
	v_add_co_u32_e32 v34, vcc, 0x13000, v30
	s_ashr_i32 s20, s65, 10
	s_nop 0
	v_addc_co_u32_e32 v35, vcc, 0, v31, vcc
	v_add_co_u32_e32 v38, vcc, 0x1d000, v30
	s_bfe_u32 s67, s65, 0x70003
	s_nop 0
	v_addc_co_u32_e32 v39, vcc, 0, v31, vcc
	v_add_co_u32_e32 v40, vcc, 0x27000, v30
	s_ashr_i32 s21, s20, 31
	s_nop 0
	v_addc_co_u32_e32 v41, vcc, 0, v31, vcc
	global_load_dwordx2 v[36:37], v[32:33], off
	global_load_dwordx2 v[30:31], v[34:35], off
	s_nop 0
	global_load_dwordx2 v[32:33], v[38:39], off
	global_load_dwordx2 v[34:35], v[40:41], off
	s_lshl_b64 s[14:15], s[20:21], 13
	s_lshl_b32 s16, s67, 6
	s_or_b32 s14, s14, s16
	s_lshl_b32 s16, s66, 8
	s_cmp_lg_u32 s67, 0
	s_cselect_b64 s[22:23], -1, 0
	v_lshl_add_u64 v[42:43], v[6:7], 0, s[14:15]
	v_lshl_add_u64 v[38:39], v[8:9], 0, s[16:17]
	s_or_b64 s[22:23], s[18:19], s[22:23]
	v_mov_b32_e32 v4, 0
	s_and_saveexec_b64 s[24:25], s[22:23]
	s_cbranch_execz .LBB0_605
	v_mad_u64_u32 v[40:41], s[70:71], v42, s27, v[38:39]
	v_mov_b32_e32 v4, v41
	v_mad_u64_u32 v[44:45], s[70:71], v43, s27, v[4:5]
	v_mov_b32_e32 v41, v44
	global_load_dword v4, v[40:41], off

; DI float bflo(unsigned w) { return __uint_as_float(w << 16); }
; DI float bfhi(unsigned w) { return __uint_as_float(w & 0xffff0000u); }
; DI float fsilu(float x) { return x * fsigmoid(x); }
; DI void ssd_prep_unit(Frame& F, const Mix1Args& a, int U) {
;     ...
;     unsigned bc[11], cc[11];
; #pragma unroll
;     for (int i = 0; i < 11; ++i) { const bool zz = (n == 0 && 8 * rg - 3 + i < 0);
;         bc[i] = zz ? 0u : *(const unsigned*)(bcol + (size_t)(r0 + i) * N3P); cc[i] = zz ? 0u : *(const unsigned*)(ccol + (size_t)(r0 + i) * N3P); }
;     { float bt[2][8];
; #pragma unroll
;       for (int i = 0; i < 8; ++i) { float vb[2], vc[2];
; #pragma unroll
;           for (int j = 0; j < 2; ++j) { float sb = bb[j], sc = cbs[j];
; #pragma unroll
;               for (int k = 0; k < 4; ++k) { sb += bw[k][j] * (j ? bfhi(bc[i + k]) : bflo(bc[i + k])); sc += cw[k][j] * (j ? bfhi(cc[i + k]) : bflo(cc[i + k])); }
;               vb[j] = fsilu(sb); vc[j] = fsilu(sc); bt[j][i] = vb[j]; }
.LBB0_617:
	s_or_b64 exec, exec, s[24:25]
	v_lshl_add_u64 v[66:67], s[14:15], 0, v[2:3]
	v_mad_u64_u32 v[68:69], s[22:23], v66, s27, v[38:39]
	v_mul_lo_u32 v67, v67, s27
	v_add_u32_e32 v69, v67, v69
	v_mad_u64_u32 v[40:41], s[22:23], v66, s27, v[40:41]
	v_add_u32_e32 v41, v67, v41
	global_load_dword v77, v[68:69], off
	global_load_dword v81, v[40:41], off
	v_lshl_add_u64 v[38:39], v[38:39], 0, v[44:45]
	v_add_co_u32_e32 v40, vcc, s28, v38
	s_waitcnt vmcnt(2)
	v_lshlrev_b32_e32 v74, 16, v64
	v_addc_co_u32_e32 v41, vcc, 0, v39, vcc
	v_add_co_u32_e32 v44, vcc, s28, v42
	v_and_b32_e32 v83, 0xffff0000, v46
	s_nop 0
	v_addc_co_u32_e32 v45, vcc, 0, v43, vcc
	v_add_co_u32_e32 v66, vcc, s29, v38
	v_and_b32_e32 v82, 0xffff0000, v4
	s_nop 0
	v_addc_co_u32_e32 v67, vcc, 0, v39, vcc
	v_add_co_u32_e32 v68, vcc, s29, v42
	v_and_b32_e32 v86, 0xffff0000, v64
	s_nop 0
	v_addc_co_u32_e32 v69, vcc, 0, v43, vcc
	v_add_co_u32_e32 v70, vcc, s30, v38
	v_lshlrev_b32_e32 v76, 16, v47
	s_nop 0
	v_addc_co_u32_e32 v71, vcc, 0, v39, vcc
	v_add_co_u32_e32 v72, vcc, s30, v42
	v_lshlrev_b32_e32 v78, 16, v65
	s_nop 0
	v_addc_co_u32_e32 v73, vcc, 0, v43, vcc
	global_load_dword v90, v[40:41], off offset:2048
	global_load_dword v91, v[44:45], off offset:2048
	global_load_dword v92, v[66:67], off offset:2560
	global_load_dword v93, v[68:69], off offset:2560
	global_load_dword v94, v[70:71], off offset:3072
	global_load_dword v95, v[72:73], off offset:3072
	v_add_co_u32_e32 v66, vcc, s31, v38
	v_and_b32_e32 v79, 0xffff0000, v65
	s_nop 0
	v_addc_co_u32_e32 v67, vcc, 0, v39, vcc
	v_add_co_u32_e32 v68, vcc, s31, v42
	s_lshl_b32 s16, s20, 7
	s_nop 0
	v_addc_co_u32_e32 v69, vcc, 0, v43, vcc
	v_add_co_u32_e32 v40, vcc, s34, v38
	s_or_b32 s20, s16, s67
	s_nop 0
	v_addc_co_u32_e32 v41, vcc, 0, v39, vcc
	v_add_co_u32_e32 v44, vcc, s34, v42
	s_ashr_i32 s21, s20, 31
	s_nop 0
	v_addc_co_u32_e32 v45, vcc, 0, v43, vcc
	v_add_co_u32_e32 v70, vcc, s35, v38
	s_lshl_b64 s[22:23], s[20:21], 16
	s_nop 0
	v_addc_co_u32_e32 v71, vcc, 0, v39, vcc
	v_add_co_u32_e32 v72, vcc, s35, v42
	s_lshl_b32 s16, s66, 13
	s_nop 0
	v_addc_co_u32_e32 v73, vcc, 0, v43, vcc
	v_add_co_u32_e32 v38, vcc, s36, v38
	s_or_b32 s20, s22, s16
	s_nop 0
	v_addc_co_u32_e32 v39, vcc, 0, v39, vcc
	v_add_co_u32_e32 v42, vcc, s36, v42
	s_mov_b32 s21, s23
	s_nop 0
	v_addc_co_u32_e32 v43, vcc, 0, v43, vcc
	global_load_dword v96, v[40:41], off
	global_load_dword v97, v[44:45], off
	global_load_dword v98, v[70:71], off offset:512
	global_load_dword v99, v[72:73], off offset:512
	global_load_dword v100, v[38:39], off offset:1024
	global_load_dword v101, v[42:43], off offset:1024
	v_lshlrev_b32_e32 v71, 16, v46
	v_lshlrev_b32_e32 v70, 16, v4
	v_mov_b32_e32 v40, v20
	v_mov_b32_e32 v41, v26
	v_pk_mul_f32 v[42:43], v[40:41], v[70:71]
	s_waitcnt vmcnt(13)
	v_lshlrev_b32_e32 v75, 16, v77
	v_mov_b32_e32 v38, v28
	v_mov_b32_e32 v39, v36
	v_add_f32_e32 v42, v18, v42
	v_pk_mul_f32 v[44:45], v[38:39], v[74:75]
	v_add_f32_e32 v42, v42, v43
	v_add_f32_e32 v42, v42, v44
	v_add_f32_e32 v70, v42, v45
	v_mul_f32_e32 v42, 0xbfb8aa3b, v70
	v_exp_f32_e32 v42, v42
	v_mov_b32_e32 v44, v21
	v_mov_b32_e32 v45, v27
	v_pk_mul_f32 v[84:85], v[44:45], v[82:83]
	v_add_f32_e32 v42, 1.0, v42
	v_rcp_f32_e32 v102, v42
	v_and_b32_e32 v87, 0xffff0000, v77
	v_mov_b32_e32 v42, v29
	v_mov_b32_e32 v43, v37
	v_add_f32_e32 v4, v19, v84
	v_pk_mul_f32 v[88:89], v[42:43], v[86:87]
	v_add_f32_e32 v4, v4, v85
	v_add_f32_e32 v4, v4, v88
	v_lshlrev_b32_e32 v72, 16, v17
	v_and_b32_e32 v73, 0xffff0000, v17
	v_add_f32_e32 v4, v4, v89
	global_load_dword v88, v[66:67], off offset:3584
	global_load_dword v89, v[68:69], off offset:3584
	v_and_b32_e32 v77, 0xffff0000, v47
	v_pk_fma_f32 v[46:47], v[24:25], v[72:73], v[22:23]
	s_waitcnt vmcnt(14)
	v_lshlrev_b32_e32 v80, 16, v81
	v_pk_fma_f32 v[46:47], v[30:31], v[76:77], v[46:47]
	v_and_b32_e32 v81, 0xffff0000, v81
	v_pk_fma_f32 v[46:47], v[32:33], v[78:79], v[46:47]
	v_mul_f32_e32 v17, 0xbfb8aa3b, v4
	v_pk_fma_f32 v[46:47], v[34:35], v[80:81], v[46:47]
	v_exp_f32_e32 v17, v17
	v_mul_f32_e32 v64, 0xbfb8aa3b, v46
	v_mul_f32_e32 v65, 0xbfb8aa3b, v47
	v_exp_f32_e32 v64, v64
	v_exp_f32_e32 v65, v65
	v_add_f32_e32 v17, 1.0, v17
	v_mov_b32_e32 v82, v71
	v_add_f32_e32 v64, 1.0, v64
	v_add_f32_e32 v65, 1.0, v65
	v_rcp_f32_e32 v64, v64
	v_rcp_f32_e32 v65, v65
	v_rcp_f32_e32 v17, v17
	v_mul_f32_e32 v102, v70, v102
	v_pk_fma_f32 v[68:69], v[20:21], v[82:83], v[18:19]
	v_mov_b32_e32 v70, v74
	v_mov_b32_e32 v71, v86
	v_pk_fma_f32 v[68:69], v[26:27], v[70:71], v[68:69]
	v_mov_b32_e32 v70, v75
	v_mov_b32_e32 v71, v87
	v_pk_mul_f32 v[46:47], v[46:47], v[64:65]
	s_waitcnt vmcnt(13)
	v_lshlrev_b32_e32 v64, 16, v90
	v_and_b32_e32 v65, 0xffff0000, v90
	v_pk_fma_f32 v[68:69], v[28:29], v[70:71], v[68:69]
	v_mul_f32_e32 v4, v4, v17
	v_pk_fma_f32 v[68:69], v[36:37], v[64:65], v[68:69]
	v_pk_fma_f32 v[76:77], v[24:25], v[76:77], v[22:23]
	v_mul_f32_e32 v17, 0xbfb8aa3b, v68
	v_exp_f32_e32 v17, v17
	v_mul_f32_e32 v67, 0xbfb8aa3b, v69
	v_exp_f32_e32 v73, v67
	v_pk_fma_f32 v[76:77], v[30:31], v[78:79], v[76:77]
	s_waitcnt vmcnt(12)
	v_lshlrev_b32_e32 v66, 16, v91
	v_and_b32_e32 v67, 0xffff0000, v91
	v_pk_fma_f32 v[76:77], v[32:33], v[80:81], v[76:77]
	v_add_f32_e32 v17, 1.0, v17
	v_pk_fma_f32 v[76:77], v[34:35], v[66:67], v[76:77]
	v_rcp_f32_e32 v72, v17
	v_add_f32_e32 v17, 1.0, v73
	v_mul_f32_e32 v73, 0xbfb8aa3b, v76
	v_exp_f32_e32 v82, v73
	v_mul_f32_e32 v73, 0xbfb8aa3b, v77
	v_exp_f32_e32 v83, v73
	v_rcp_f32_e32 v73, v17
	v_add_f32_e32 v17, 1.0, v82
	v_rcp_f32_e32 v82, v17
	v_add_f32_e32 v17, 1.0, v83
	v_rcp_f32_e32 v83, v17
	v_cvt_pk_bf16_f32 v84, v46, v47
	v_pk_mul_f32 v[46:47], v[68:69], v[72:73]
	v_cvt_pk_bf16_f32 v17, v102, v4
	v_cvt_pk_bf16_f32 v72, v46, v47
	v_add_u32_e32 v90, 0x4800, v48
	ds_write2_b32 v90, v17, v72 offset1:72
	v_pk_fma_f32 v[72:73], v[24:25], v[78:79], v[22:23]
	v_pk_mul_f32 v[68:69], v[76:77], v[82:83]
	v_pk_fma_f32 v[72:73], v[30:31], v[80:81], v[72:73]
	v_cvt_pk_bf16_f32 v17, v68, v69
	s_waitcnt vmcnt(10)
; #define LAS __attribute__((address_space(3)))
; DI float bflo(unsigned w) { return __uint_as_float(w << 16); }
; DI float bfhi(unsigned w) { return __uint_as_float(w & 0xffff0000u); }
; DI unsigned pk2(float lo, float hi) { f32x2 v = {lo, hi}; bf16v2 b = __builtin_convertvector(v, bf16v2); return __builtin_bit_cast(unsigned, b); }
; DI float fsilu(float x) { return x * fsigmoid(x); }
; DI void ssd_prep_unit(Frame& F, const Mix1Args& a, int U) {
;     ...
;       for (int i = 0; i < 8; ++i) { float vb[2], vc[2];
; #pragma unroll
;           for (int j = 0; j < 2; ++j) { float sb = bb[j], sc = cbs[j];
; #pragma unroll
;               for (int k = 0; k < 4; ++k) { sb += bw[k][j] * (j ? bfhi(bc[i + k]) : bflo(bc[i + k])); sc += cw[k][j] * (j ? bfhi(cc[i + k]) : bflo(cc[i + k])); }
;               vb[j] = fsilu(sb); vc[j] = fsilu(sc); bt[j][i] = vb[j]; }
;           *(LAS unsigned*)(BC + (8 * rg + i) * S128 + c2 * 4) = pk2(vb[0], vb[1]);
;           *(LAS unsigned*)(CC + (8 * rg + i) * S128 + c2 * 4) = pk2(vc[0], vc[1]); }
	v_lshlrev_b32_e32 v68, 16, v93
	v_and_b32_e32 v69, 0xffff0000, v93
	v_pk_fma_f32 v[72:73], v[32:33], v[66:67], v[72:73]
	ds_write2_b32 v48, v84, v17 offset1:72
	v_pk_fma_f32 v[72:73], v[34:35], v[68:69], v[72:73]
	v_pk_mul_f32 v[74:75], v[40:41], v[74:75]
	v_mul_f32_e32 v17, 0xbfb8aa3b, v72
	v_exp_f32_e32 v17, v17
	v_mul_f32_e32 v76, 0xbfb8aa3b, v73
	v_exp_f32_e32 v77, v76
	v_lshlrev_b32_e32 v78, 16, v92
	v_add_f32_e32 v17, 1.0, v17
	v_rcp_f32_e32 v76, v17
	v_add_f32_e32 v17, 1.0, v77
	v_rcp_f32_e32 v77, v17
	v_add_f32_e32 v17, v18, v74
	v_add_f32_e32 v17, v17, v75
	v_pk_mul_f32 v[82:83], v[44:45], v[86:87]
	v_pk_mul_f32 v[72:73], v[72:73], v[76:77]
	v_mov_b32_e32 v76, v64
	v_mov_b32_e32 v77, v78
	v_pk_mul_f32 v[84:85], v[38:39], v[76:77]
	v_and_b32_e32 v79, 0xffff0000, v92
	v_add_f32_e32 v17, v17, v84
	v_add_f32_e32 v17, v17, v85
	v_mul_f32_e32 v74, 0xbfb8aa3b, v17
	v_exp_f32_e32 v75, v74
	v_cvt_pk_bf16_f32 v91, v72, v73
	v_mov_b32_e32 v84, v65
	v_mov_b32_e32 v85, v79
	v_add_f32_e32 v73, 1.0, v75
	v_rcp_f32_e32 v92, v73
	v_add_f32_e32 v73, v19, v82
	v_pk_mul_f32 v[86:87], v[42:43], v[84:85]
	v_add_f32_e32 v73, v73, v83
	v_add_f32_e32 v73, v73, v86
	v_add_f32_e32 v86, v73, v87
	v_mul_f32_e32 v73, 0xbfb8aa3b, v86
	v_exp_f32_e32 v82, v73
	v_pk_fma_f32 v[70:71], v[20:21], v[70:71], v[18:19]
	v_pk_fma_f32 v[80:81], v[24:25], v[80:81], v[22:23]
	v_pk_fma_f32 v[64:65], v[26:27], v[64:65], v[70:71]
	v_pk_fma_f32 v[80:81], v[30:31], v[66:67], v[80:81]
	s_waitcnt vmcnt(9)
	v_lshlrev_b32_e32 v72, 16, v94
	s_waitcnt vmcnt(8)
	v_lshlrev_b32_e32 v74, 16, v95
	v_and_b32_e32 v73, 0xffff0000, v94
	v_and_b32_e32 v75, 0xffff0000, v95
	v_pk_fma_f32 v[64:65], v[28:29], v[78:79], v[64:65]
	v_pk_fma_f32 v[80:81], v[32:33], v[68:69], v[80:81]
	v_add_f32_e32 v82, 1.0, v82
	v_pk_fma_f32 v[64:65], v[36:37], v[72:73], v[64:65]
	v_pk_fma_f32 v[80:81], v[34:35], v[74:75], v[80:81]
	v_mul_f32_e32 v70, 0xbfb8aa3b, v64
	v_mul_f32_e32 v71, 0xbfb8aa3b, v65
	v_rcp_f32_e32 v87, v82
	v_mul_f32_e32 v82, 0xbfb8aa3b, v80
	v_mul_f32_e32 v83, 0xbfb8aa3b, v81
	v_exp_f32_e32 v70, v70
	v_exp_f32_e32 v71, v71
	v_exp_f32_e32 v82, v82
	v_exp_f32_e32 v83, v83
	v_add_f32_e32 v70, 1.0, v70
	v_add_f32_e32 v71, 1.0, v71
	v_add_f32_e32 v82, 1.0, v82
	v_add_f32_e32 v83, 1.0, v83
	v_rcp_f32_e32 v70, v70
	v_rcp_f32_e32 v71, v71
	v_rcp_f32_e32 v82, v82
	v_rcp_f32_e32 v83, v83
	v_pk_fma_f32 v[66:67], v[24:25], v[66:67], v[22:23]
	v_pk_mul_f32 v[64:65], v[64:65], v[70:71]
	v_pk_fma_f32 v[66:67], v[30:31], v[68:69], v[66:67]
	v_pk_mul_f32 v[70:71], v[80:81], v[82:83]
	v_mul_f32_e32 v17, v17, v92
	v_cvt_pk_bf16_f32 v70, v70, v71
	v_mul_f32_e32 v92, v86, v87
	ds_write2_b32 v48, v91, v70 offset0:144 offset1:216
	s_waitcnt vmcnt(0)
	v_lshlrev_b32_e32 v70, 16, v89
	v_and_b32_e32 v71, 0xffff0000, v89
	v_pk_fma_f32 v[66:67], v[32:33], v[74:75], v[66:67]
	v_cvt_pk_bf16_f32 v86, v17, v92
	v_cvt_pk_bf16_f32 v80, v64, v65
	v_pk_fma_f32 v[66:67], v[34:35], v[70:71], v[66:67]
	ds_write2_b32 v90, v86, v80 offset0:144 offset1:216
	v_mul_f32_e32 v80, 0xbfb8aa3b, v66
	v_mul_f32_e32 v81, 0xbfb8aa3b, v67
	v_exp_f32_e32 v80, v80
	v_exp_f32_e32 v81, v81
	v_pk_mul_f32 v[76:77], v[40:41], v[76:77]
	v_lshlrev_b32_e32 v82, 16, v88
	v_add_f32_e32 v80, 1.0, v80
	v_add_f32_e32 v81, 1.0, v81
	v_rcp_f32_e32 v80, v80
	v_rcp_f32_e32 v81, v81
	v_add_f32_e32 v76, v18, v76
	v_add_f32_e32 v76, v76, v77
	v_pk_mul_f32 v[84:85], v[44:45], v[84:85]
	v_pk_mul_f32 v[66:67], v[66:67], v[80:81]
	v_mov_b32_e32 v80, v72
	v_mov_b32_e32 v81, v82
	v_pk_mul_f32 v[86:87], v[38:39], v[80:81]
	v_and_b32_e32 v83, 0xffff0000, v88
	v_add_f32_e32 v76, v76, v86
	v_add_f32_e32 v90, v76, v87
	v_mul_f32_e32 v76, 0xbfb8aa3b, v90
	v_exp_f32_e32 v77, v76
	v_cvt_pk_bf16_f32 v91, v66, v67
	v_mov_b32_e32 v86, v73
	v_mov_b32_e32 v87, v83
	v_add_f32_e32 v67, 1.0, v77
	v_rcp_f32_e32 v93, v67
	v_add_f32_e32 v67, v19, v84
	v_pk_mul_f32 v[88:89], v[42:43], v[86:87]
	v_add_f32_e32 v67, v67, v85
	v_add_f32_e32 v67, v67, v88
	v_add_f32_e32 v88, v67, v89
	v_mul_f32_e32 v67, 0xbfb8aa3b, v88
	v_exp_f32_e32 v84, v67
	v_pk_fma_f32 v[68:69], v[24:25], v[68:69], v[22:23]
	v_lshlrev_b32_e32 v76, 16, v97
	v_pk_fma_f32 v[68:69], v[30:31], v[74:75], v[68:69]
	v_and_b32_e32 v77, 0xffff0000, v97
	v_pk_fma_f32 v[78:79], v[20:21], v[78:79], v[18:19]
	v_pk_fma_f32 v[68:69], v[32:33], v[70:71], v[68:69]
	v_add_f32_e32 v84, 1.0, v84
	v_pk_fma_f32 v[72:73], v[26:27], v[72:73], v[78:79]
	v_pk_fma_f32 v[68:69], v[34:35], v[76:77], v[68:69]
	v_lshlrev_b32_e32 v66, 16, v96
	v_and_b32_e32 v67, 0xffff0000, v96
	v_mul_f32_e32 v89, v90, v93
	v_pk_fma_f32 v[72:73], v[28:29], v[82:83], v[72:73]
	v_rcp_f32_e32 v90, v84
	v_mul_f32_e32 v84, 0xbfb8aa3b, v68
	v_mul_f32_e32 v85, 0xbfb8aa3b, v69
	v_pk_fma_f32 v[72:73], v[36:37], v[66:67], v[72:73]
	v_exp_f32_e32 v84, v84
	v_exp_f32_e32 v85, v85
	v_mul_f32_e32 v78, 0xbfb8aa3b, v72
	v_mul_f32_e32 v79, 0xbfb8aa3b, v73
	v_exp_f32_e32 v78, v78
	v_exp_f32_e32 v79, v79
	v_add_f32_e32 v84, 1.0, v84
	v_add_f32_e32 v85, 1.0, v85
	v_rcp_f32_e32 v84, v84
	v_rcp_f32_e32 v85, v85
	v_add_f32_e32 v78, 1.0, v78
	v_add_f32_e32 v79, 1.0, v79
	v_rcp_f32_e32 v78, v78
	v_rcp_f32_e32 v79, v79
	v_pk_mul_f32 v[68:69], v[68:69], v[84:85]
	v_pk_fma_f32 v[74:75], v[24:25], v[74:75], v[22:23]
	v_cvt_pk_bf16_f32 v68, v68, v69
	v_add_u32_e32 v85, 0x400, v48
	v_pk_fma_f32 v[74:75], v[30:31], v[70:71], v[74:75]
	v_mul_f32_e32 v88, v88, v90
	v_pk_mul_f32 v[72:73], v[72:73], v[78:79]
	ds_write2_b32 v85, v91, v68 offset0:32 offset1:104
	v_lshlrev_b32_e32 v68, 16, v99
	v_and_b32_e32 v69, 0xffff0000, v99
	v_pk_fma_f32 v[74:75], v[32:33], v[76:77], v[74:75]
	v_cvt_pk_bf16_f32 v90, v89, v88
; #define LAS __attribute__((address_space(3)))
; DI unsigned pk2(float lo, float hi) { f32x2 v = {lo, hi}; bf16v2 b = __builtin_convertvector(v, bf16v2); return __builtin_bit_cast(unsigned, b); }
; #define LDS_BAR() do { asm volatile("s_waitcnt lgkmcnt(0)" ::: "memory"); __builtin_amdgcn_s_barrier(); asm volatile("" ::: "memory"); } while (0)
; DI void ssd_prep_unit(Frame& F, const Mix1Args& a, int U) {
;     ...
; #pragma unroll
;       for (int j = 0; j < 2; ++j) { u32x4 p; p.x = pk2(bt[j][0], bt[j][1]); p.y = pk2(bt[j][2], bt[j][3]); p.z = pk2(bt[j][4], bt[j][5]); p.w = pk2(bt[j][6], bt[j][7]);
;           *(LAS u32x4*)(BT + (2 * c2 + j) * S64 + rg * 16) = p; } }
;     LDS_BAR();
;     const size_t T = ((size_t)(b * 128 + n)) * 8 + g;
; #pragma unroll
;     for (int i = 0; i < 2; ++i) { const int c = tid + 512 * i, ln = c & 63;
;         *(u32x4*)(a.Cg + T * 8192 + (size_t)c * 8) = *(const LAS u32x4*)(CC + (16 * (c >> 8) + (ln & 15)) * S128 + ((c >> 6) & 3) * 64 + (ln >> 4) * 16);
;         *(u32x4*)(a.BTg + T * 8192 + (size_t)c * 8) = *(const LAS u32x4*)(BT + (16 * (c >> 7) + (ln & 15)) * S64 + ((c >> 6) & 1) * 64 + (ln >> 4) * 16); }
;     { const int l0_ = 16 * (w & 3);
; #pragma unroll
;       for (int t = 0; t < 2; ++t) { const int m0 = 16 * ((w >> 2) * 2 + t);
;           const f32x4 cbv = mma_tile<4>((f32x4){0.f, 0.f, 0.f, 0.f}, BC, S128, m0, CC, S128, l0_, fr, fq);
;           u32x2 p; p.x = pk2(cbv[0], cbv[1]); p.y = pk2(cbv[2], cbv[3]);
;           *(u32x2*)(a.CBg + T * 4096 + (size_t)(l0_ + fr) * 64 + m0 + 4 * fq) = p; } }
; #pragma unroll
;     for (int t = 0; t < 2; ++t) { const int h = 16 * g + 2 * w + t;
;         const size_t di = ((size_t)b * SEQ + (size_t)n * 64 + lane) * 128 + h; const size_t dq = (size_t)16384 * 128;
;         const float xx = ((a.dtp[di] + a.dtp[di + dq]) + (a.dtp[di + 2 * dq] + a.dtp[di + 3 * dq])) + a.dt_bias[h];
;         const float dtv = xx > 20.f ? xx : log1pf(__expf(xx)); float cs = dtv * (-__expf(a.a_log[h]) * LOG2E);
	v_cvt_pk_bf16_f32 v78, v72, v73
	v_add_u32_e32 v84, 0x4c00, v48
	v_pk_fma_f32 v[74:75], v[34:35], v[68:69], v[74:75]
	ds_write2_b32 v84, v90, v78 offset0:32 offset1:104
	v_mul_f32_e32 v78, 0xbfb8aa3b, v74
	v_mul_f32_e32 v79, 0xbfb8aa3b, v75
	v_exp_f32_e32 v78, v78
	v_exp_f32_e32 v79, v79
	v_pk_mul_f32 v[40:41], v[40:41], v[80:81]
	v_lshlrev_b32_e32 v80, 16, v98
	v_add_f32_e32 v78, 1.0, v78
	v_add_f32_e32 v79, 1.0, v79
	v_rcp_f32_e32 v78, v78
	v_rcp_f32_e32 v79, v79
	v_add_f32_e32 v40, v18, v40
	v_add_f32_e32 v40, v40, v41
	v_pk_mul_f32 v[44:45], v[44:45], v[86:87]
	v_pk_mul_f32 v[74:75], v[74:75], v[78:79]
	v_mov_b32_e32 v78, v66
	v_mov_b32_e32 v79, v80
	v_pk_mul_f32 v[38:39], v[38:39], v[78:79]
	v_and_b32_e32 v81, 0xffff0000, v98
	v_add_f32_e32 v38, v40, v38
	v_add_f32_e32 v78, v38, v39
	v_mul_f32_e32 v38, 0xbfb8aa3b, v78
	v_exp_f32_e32 v39, v38
	v_cvt_pk_bf16_f32 v79, v74, v75
	v_mov_b32_e32 v74, v67
	v_mov_b32_e32 v75, v81
	v_add_f32_e32 v39, 1.0, v39
	v_rcp_f32_e32 v86, v39
	v_add_f32_e32 v39, v19, v44
	v_pk_mul_f32 v[42:43], v[42:43], v[74:75]
	v_add_f32_e32 v39, v39, v45
	v_add_f32_e32 v39, v39, v42
	v_add_f32_e32 v42, v39, v43
	v_pk_fma_f32 v[18:19], v[20:21], v[82:83], v[18:19]
	v_pk_fma_f32 v[22:23], v[24:25], v[70:71], v[22:23]
	v_mul_f32_e32 v39, 0xbfb8aa3b, v42
	v_pk_fma_f32 v[18:19], v[26:27], v[66:67], v[18:19]
	v_pk_fma_f32 v[22:23], v[30:31], v[76:77], v[22:23]
	v_lshlrev_b32_e32 v38, 16, v100
	v_lshlrev_b32_e32 v40, 16, v101
	v_exp_f32_e32 v43, v39
	v_and_b32_e32 v39, 0xffff0000, v100
	v_and_b32_e32 v41, 0xffff0000, v101
	v_pk_fma_f32 v[18:19], v[28:29], v[80:81], v[18:19]
	v_pk_fma_f32 v[22:23], v[32:33], v[68:69], v[22:23]
	v_pk_fma_f32 v[18:19], v[36:37], v[38:39], v[18:19]
	v_pk_fma_f32 v[22:23], v[34:35], v[40:41], v[22:23]
	v_mul_f32_e32 v20, 0xbfb8aa3b, v18
	v_mul_f32_e32 v21, 0xbfb8aa3b, v19
	v_mul_f32_e32 v24, 0xbfb8aa3b, v22
	v_mul_f32_e32 v25, 0xbfb8aa3b, v23
	v_exp_f32_e32 v20, v20
	v_exp_f32_e32 v21, v21
	v_exp_f32_e32 v24, v24
	v_exp_f32_e32 v25, v25
	v_add_f32_e32 v43, 1.0, v43
	v_add_f32_e32 v20, 1.0, v20
	v_add_f32_e32 v21, 1.0, v21
	v_add_f32_e32 v24, 1.0, v24
	v_add_f32_e32 v25, 1.0, v25
	v_rcp_f32_e32 v26, v43
	v_rcp_f32_e32 v20, v20
	v_rcp_f32_e32 v21, v21
	v_rcp_f32_e32 v24, v24
	v_rcp_f32_e32 v25, v25
	v_mul_f32_e32 v44, v78, v86
	v_mul_f32_e32 v28, v42, v26
	v_pk_mul_f32 v[26:27], v[18:19], v[20:21]
	v_pk_mul_f32 v[18:19], v[22:23], v[24:25]
	v_cvt_pk_bf16_f32 v29, v44, v28
	v_cvt_pk_bf16_f32 v20, v26, v27
	v_cvt_pk_bf16_f32 v18, v18, v19
	ds_write2_b32 v84, v29, v20 offset0:176 offset1:248
	ds_write2_b32 v85, v79, v18 offset0:176 offset1:248
	v_cvt_pk_bf16_f32 v18, v102, v46
	v_cvt_pk_bf16_f32 v19, v17, v64
	v_cvt_pk_bf16_f32 v20, v89, v72
	v_cvt_pk_bf16_f32 v21, v44, v26
	ds_write_b128 v49, v[18:21] offset:36864
	v_cvt_pk_bf16_f32 v18, v4, v47
	v_cvt_pk_bf16_f32 v19, v92, v65
	v_cvt_pk_bf16_f32 v20, v88, v73
	v_cvt_pk_bf16_f32 v21, v28, v27
	ds_write_b128 v49, v[18:21] offset:37024
	s_waitcnt lgkmcnt(0)
	s_barrier
	ds_read_b128 v[18:21], v56 offset:18432
	ds_read_b128 v[22:25], v57
	ds_read_b128 v[26:29], v56 offset:18496
	ds_read_b128 v[30:33], v57 offset:64
	ds_read_b128 v[34:37], v56 offset:18560
	s_waitcnt lgkmcnt(3)
	v_mfma_f32_16x16x32_bf16 v[18:21], v[18:21], v[22:25], 0
	ds_read_b128 v[38:41], v50
	ds_read_b128 v[42:45], v57 offset:128
	ds_read_b128 v[64:67], v56 offset:18624
	s_lshl_b64 s[24:25], s[20:21], 1
	s_add_u32 s68, s3, s24
	s_waitcnt lgkmcnt(4)
	v_mfma_f32_16x16x32_bf16 v[18:21], v[26:29], v[30:33], v[18:21]
	ds_read_b128 v[26:29], v57 offset:192
	ds_read_b128 v[68:71], v52 offset:36864
	s_addc_u32 s69, s33, s25
	s_waitcnt lgkmcnt(3)
	v_mfma_f32_16x16x32_bf16 v[18:21], v[34:37], v[42:45], v[18:21]
	ds_read_b128 v[34:37], v58 offset:18432
	global_store_dwordx4 v51, v[38:41], s[68:69]
	ds_read_b128 v[38:41], v58 offset:18496
	s_waitcnt lgkmcnt(3)
	v_mfma_f32_16x16x32_bf16 v[18:21], v[64:67], v[26:29], v[18:21]
	ds_read_b128 v[64:67], v58 offset:18560
	s_add_u32 s24, s84, s24
	s_addc_u32 s25, s85, s25
	s_waitcnt lgkmcnt(2)
	v_mfma_f32_16x16x32_bf16 v[22:25], v[34:37], v[22:25], 0
	ds_read_b128 v[34:37], v53
	ds_read_b128 v[72:75], v55 offset:36864
	global_store_dwordx4 v51, v[68:71], s[24:25]
	ds_read_b128 v[68:71], v58 offset:18624
	s_waitcnt lgkmcnt(4)
	v_mfma_f32_16x16x32_bf16 v[22:25], v[38:41], v[30:33], v[22:25]
	v_cvt_pk_bf16_f32 v18, v18, v19
	v_cvt_pk_bf16_f32 v19, v20, v21
	v_lshl_add_u64 v[30:31], v[14:15], 0, s[20:21]
	s_waitcnt lgkmcnt(3)
	v_mfma_f32_16x16x32_bf16 v[22:25], v[64:67], v[42:45], v[22:25]
	s_waitcnt lgkmcnt(2)
	global_store_dwordx4 v54, v[34:37], s[68:69]
	s_waitcnt lgkmcnt(1)
	global_store_dwordx4 v54, v[72:75], s[24:25]
	global_store_dwordx2 v[30:31], v[18:19], off
	s_lshl_b32 s16, s66, 4
	s_waitcnt lgkmcnt(0)
	v_mfma_f32_16x16x32_bf16 v[18:21], v[68:71], v[26:29], v[22:25]
	s_add_i32 s16, s16, s26
	s_nop 6
	v_cvt_pk_bf16_f32 v18, v18, v19
	v_cvt_pk_bf16_f32 v19, v20, v21
	global_store_dwordx2 v[30:31], v[18:19], off offset:32
	v_mov_b32_e32 v19, s15
	v_or_b32_e32 v18, s14, v166
	v_lshlrev_b64 v[18:19], 9, v[18:19]
	v_lshl_add_u64 v[18:19], s[82:83], 0, v[18:19]
	s_lshl_b32 s14, s16, 2
	s_mov_b32 s15, s17
	v_lshl_add_u64 v[20:21], v[18:19], 0, s[14:15]
	v_add_co_u32_e32 v22, vcc, s37, v20
	v_mov_b32_e32 v4, s14
	s_nop 0
	v_addc_co_u32_e32 v23, vcc, 0, v21, vcc
	v_add_co_u32_e32 v24, vcc, s38, v20
	s_add_u32 s20, s44, s14
	s_nop 0
	v_addc_co_u32_e32 v25, vcc, 0, v21, vcc
	v_add_co_u32_e32 v18, vcc, s39, v20
	s_addc_u32 s21, s45, 0
	s_nop 0
	v_addc_co_u32_e32 v19, vcc, 0, v21, vcc
	v_mov_b32_e32 v26, v112
	v_mov_b32_e32 v28, v113
	v_mov_b32_e32 v27, v114
	v_mov_b32_e32 v29, v115
	s_waitcnt vmcnt(0)
	v_pk_add_f32 v[18:19], v[26:27], v[28:29]
	v_mov_b32_e32 v4, v120
	v_add_f32_e32 v17, v18, v19
	s_waitcnt vmcnt(0)
	v_add_f32_e32 v17, v4, v17
	v_cmp_nlt_f32_e32 vcc, s40, v17
	s_and_saveexec_b64 s[14:15], vcc
	s_cbranch_execz .LBB0_619
; DI void ssd_prep_unit(Frame& F, const Mix1Args& a, int U) {
;     ...
;         const float xx = ((a.dtp[di] + a.dtp[di + dq]) + (a.dtp[di + 2 * dq] + a.dtp[di + 3 * dq])) + a.dt_bias[h];
;         const float dtv = xx > 20.f ? xx : log1pf(__expf(xx)); float cs = dtv * (-__expf(a.a_log[h]) * LOG2E);
	v_mul_f32_e32 v4, 0x3fb8aa3b, v17
	v_exp_f32_e32 v4, v4
	s_nop 0
	v_add_f32_e32 v17, 1.0, v4
	v_frexp_mant_f32_e32 v27, v17
	v_cvt_f64_f32_e32 v[18:19], v17
	v_add_f32_e32 v26, -1.0, v17
	v_frexp_exp_i32_f64_e32 v18, v[18:19]
	v_cmp_gt_f32_e32 vcc, s41, v27
	v_sub_f32_e32 v28, v26, v17
	v_sub_f32_e32 v26, v4, v26
	v_subbrev_co_u32_e32 v32, vcc, 0, v18, vcc
	v_add_f32_e32 v28, 1.0, v28
	v_sub_u32_e32 v18, 0, v32
	v_add_f32_e32 v26, v26, v28
	v_ldexp_f32 v17, v17, v18
	v_ldexp_f32 v18, v26, v18
	v_add_f32_e32 v26, -1.0, v17
	v_add_f32_e32 v19, 1.0, v26
	v_sub_f32_e32 v19, v17, v19
	v_add_f32_e32 v27, v18, v19
	v_add_f32_e32 v19, 1.0, v17
	v_add_f32_e32 v28, -1.0, v19
	v_sub_f32_e32 v17, v17, v28
	v_add_f32_e32 v17, v18, v17
	v_add_f32_e32 v33, v19, v17
	v_rcp_f32_e32 v34, v33
	v_sub_f32_e32 v18, v33, v19
	v_add_f32_e32 v19, v26, v27
	v_sub_f32_e32 v17, v17, v18
	v_mul_f32_e32 v36, v19, v34
	v_sub_f32_e32 v18, v19, v26
	v_mul_f32_e32 v26, v33, v36
	v_fma_f32 v28, v36, v33, -v26
	v_fmac_f32_e32 v28, v36, v17
	v_sub_f32_e32 v35, v27, v18
	v_add_f32_e32 v18, v26, v28
	v_sub_f32_e32 v27, v19, v18
	v_pk_add_f32 v[30:31], v[18:19], v[26:27] neg_lo:[0,1] neg_hi:[0,1]
	v_mov_b32_e32 v29, v18
	v_pk_add_f32 v[18:19], v[30:31], v[28:29] neg_lo:[0,1] neg_hi:[0,1]
	v_cmp_neq_f32_e32 vcc, s63, v4
	v_add_f32_e32 v19, v35, v19
	v_add_f32_e32 v18, v18, v19
	v_add_f32_e32 v19, v27, v18
	v_mul_f32_e32 v35, v34, v19
	v_mul_f32_e32 v26, v33, v35
	v_fma_f32 v28, v35, v33, -v26
	v_fmac_f32_e32 v28, v35, v17
	v_sub_f32_e32 v17, v27, v19
	v_add_f32_e32 v17, v18, v17
	v_add_f32_e32 v18, v26, v28
	v_sub_f32_e32 v27, v19, v18
	v_pk_add_f32 v[30:31], v[18:19], v[26:27] neg_lo:[0,1] neg_hi:[0,1]
	v_mov_b32_e32 v29, v18
	v_pk_add_f32 v[18:19], v[30:31], v[28:29] neg_lo:[0,1] neg_hi:[0,1]
	s_nop 0
	v_add_f32_e32 v17, v17, v19
	v_add_f32_e32 v17, v18, v17
	v_add_f32_e32 v19, v36, v35
	v_add_f32_e32 v17, v27, v17
	v_sub_f32_e32 v18, v19, v36
	v_mul_f32_e32 v17, v34, v17
	v_sub_f32_e32 v18, v35, v18
	v_add_f32_e32 v26, v18, v17
	v_add_f32_e32 v28, v19, v26
	v_cvt_f32_i32_e32 v18, v32
	v_mul_f32_e32 v29, v28, v28
	v_sub_f32_e32 v19, v28, v19
	v_fmamk_f32 v17, v29, 0x3e9b6dac, v59
	v_sub_f32_e32 v19, v26, v19
	v_fmaak_f32 v17, v29, v17, 0x3f2aaada
	v_ldexp_f32 v30, v19, 1
	v_mul_f32_e32 v19, v28, v29
	v_ldexp_f32 v27, v28, 1
	v_pk_mul_f32 v[28:29], v[18:19], v[16:17]
	s_nop 0
	v_fma_f32 v26, v18, s62, -v28
	v_fmac_f32_e32 v26, 0xb102e308, v18
	v_pk_add_f32 v[18:19], v[28:29], v[26:27]
	s_nop 0
	v_sub_f32_e32 v17, v19, v27
	v_sub_f32_e32 v17, v29, v17
	v_add_f32_e32 v31, v30, v17
	v_mov_b32_e32 v30, v28
	v_pk_add_f32 v[28:29], v[18:19], v[28:29] neg_lo:[0,1] neg_hi:[0,1]
	v_pk_add_f32 v[32:33], v[18:19], v[30:31]
	v_mov_b32_e32 v27, v18
	v_mov_b32_e32 v29, v33
	v_pk_add_f32 v[34:35], v[26:27], v[28:29] neg_lo:[0,1] neg_hi:[0,1]
	v_pk_add_f32 v[26:27], v[26:27], v[28:29]
	v_mov_b32_e32 v30, v31
	v_pk_add_f32 v[28:29], v[26:27], v[18:19] op_sel:[1,0] op_sel_hi:[0,1] neg_lo:[0,1] neg_hi:[0,1]
	v_pk_add_f32 v[36:37], v[32:33], v[28:29] op_sel_hi:[1,0] neg_lo:[0,1] neg_hi:[0,1]
	v_mov_b32_e32 v32, v33
	v_mov_b32_e32 v33, v27
	v_pk_mov_b32 v[28:29], v[18:19], v[28:29] op_sel:[1,0]
	v_mov_b32_e32 v31, v18
	v_pk_add_f32 v[28:29], v[32:33], v[28:29] neg_lo:[0,1] neg_hi:[0,1]
	v_mov_b32_e32 v36, v34
	v_pk_add_f32 v[18:19], v[30:31], v[28:29] neg_lo:[0,1] neg_hi:[0,1]
	v_mov_b32_e32 v35, v27
	v_pk_add_f32 v[28:29], v[36:37], v[18:19]
	s_nop 0
	v_pk_add_f32 v[30:31], v[28:29], v[28:29] op_sel:[0,1] op_sel_hi:[1,0]
	s_nop 0
	v_pk_add_f32 v[26:27], v[26:27], v[30:31] op_sel:[1,0] op_sel_hi:[0,1]
	v_mov_b32_e32 v29, v26
	v_pk_add_f32 v[32:33], v[28:29], v[34:35] neg_lo:[0,1] neg_hi:[0,1]
	v_mov_b32_e32 v19, v30
	v_sub_f32_e32 v17, v28, v32
	v_pk_add_f32 v[18:19], v[18:19], v[32:33] neg_lo:[0,1] neg_hi:[0,1]
	v_sub_f32_e32 v17, v34, v17
	v_add_f32_e32 v17, v18, v17
	v_add_f32_e32 v17, v17, v19
	v_add_f32_e32 v17, v26, v17
	v_cndmask_b32_e32 v17, v61, v17, vcc
	v_cmp_ngt_f32_e32 vcc, -1.0, v4
	s_nop 1
	v_cndmask_b32_e32 v17, v62, v17, vcc
	v_cmp_neq_f32_e32 vcc, -1.0, v4
	s_nop 1
	v_cndmask_b32_e32 v17, v63, v17, vcc
	v_cmp_lt_f32_e64 vcc, |v4|, s64
	s_nop 1
	v_cndmask_b32_e32 v17, v17, v4, vcc
; DI void ssd_prep_unit(Frame& F, const Mix1Args& a, int U) {
;     ...
; #pragma unroll
;     for (int t = 0; t < 2; ++t) { const int h = 16 * g + 2 * w + t;
;         const size_t di = ((size_t)b * SEQ + (size_t)n * 64 + lane) * 128 + h; const size_t dq = (size_t)16384 * 128;
;         const float xx = ((a.dtp[di] + a.dtp[di + dq]) + (a.dtp[di + 2 * dq] + a.dtp[di + 3 * dq])) + a.dt_bias[h];
;         const float dtv = xx > 20.f ? xx : log1pf(__expf(xx)); float cs = dtv * (-__expf(a.a_log[h]) * LOG2E);
; #pragma unroll
;         for (int o = 1; o < 64; o <<= 1) { const float tt = __shfl_up(cs, o); if (lane >= o) cs += tt; }
;         float* tp = a.TABg + (((size_t)(b * 128 + n)) * 128 + h) * 128; tp[lane] = cs; tp[64 + lane] = dtv; }
.LBB0_619:
	s_or_b64 exec, exec, s[14:15]
	s_lshl_b32 s24, s16, 2
	v_mov_b32_e32 v4, s24
	v_mov_b32_e32 v4, v122
	v_and_b32_e32 v27, 64, v60
	v_add_u32_e32 v26, -1, v60
	v_cmp_lt_i32_e32 vcc, v26, v27
	v_add_u32_e32 v28, -2, v60
	v_add_u32_e32 v29, -4, v60
	v_cmp_lt_i32_e64 s[14:15], v29, v27
	v_add_u32_e32 v30, -8, v60
	v_add_u32_e32 v31, -16, v60
	v_subrev_u32_e32 v35, 32, v60
	v_lshl_add_u64 v[18:19], v[12:13], 0, s[22:23]
	s_add_u32 s22, s46, s24
	s_addc_u32 s23, s47, 0
	s_waitcnt vmcnt(0)
	v_mul_f32_e32 v4, 0x3fb8aa3b, v4
	v_exp_f32_e32 v32, v4
	v_cndmask_b32_e32 v4, v26, v60, vcc
	v_lshlrev_b32_e32 v4, 2, v4
	v_cmp_lt_i32_e32 vcc, v28, v27
	v_mul_f32_e32 v32, 0xbfb8aa3b, v32
	v_mul_f32_e32 v33, v17, v32
	ds_bpermute_b32 v34, v4, v33
	v_cndmask_b32_e32 v26, v28, v60, vcc
	v_lshlrev_b32_e32 v26, 2, v26
	v_cndmask_b32_e64 v28, v29, v60, s[14:15]
	v_lshlrev_b32_e32 v28, 2, v28
	s_waitcnt lgkmcnt(0)
	v_fmac_f32_e32 v34, v17, v32
	v_cndmask_b32_e64 v33, v34, v33, s[0:1]
	ds_bpermute_b32 v34, v26, v33
	v_cmp_lt_i32_e64 s[14:15], v30, v27
	v_add_co_u32_e32 v32, vcc, 0x1800000, v20
	s_waitcnt lgkmcnt(0)
	v_add_f32_e32 v29, v33, v34
	v_cndmask_b32_e64 v33, v29, v33, s[12:13]
	ds_bpermute_b32 v34, v28, v33
	v_cndmask_b32_e64 v29, v30, v60, s[14:15]
	v_lshlrev_b32_e32 v29, 2, v29
	v_cmp_lt_i32_e64 s[14:15], v31, v27
	s_waitcnt lgkmcnt(0)
	v_add_f32_e32 v30, v33, v34
	v_cndmask_b32_e64 v33, v30, v33, s[4:5]
	ds_bpermute_b32 v34, v29, v33
	v_cndmask_b32_e64 v30, v31, v60, s[14:15]
	v_lshlrev_b32_e32 v30, 2, v30
	v_cmp_lt_i32_e64 s[14:15], v35, v27
	s_waitcnt lgkmcnt(0)
	v_add_f32_e32 v31, v33, v34
	v_cndmask_b32_e64 v31, v31, v33, s[6:7]
	ds_bpermute_b32 v34, v30, v31
	v_cndmask_b32_e64 v27, v35, v60, s[14:15]
	v_lshlrev_b32_e32 v27, 2, v27
	s_lshl_b64 s[14:15], s[16:17], 9
	v_addc_co_u32_e32 v33, vcc, 0, v21, vcc
	s_waitcnt lgkmcnt(0)
	v_add_f32_e32 v34, v31, v34
	v_cndmask_b32_e64 v31, v34, v31, s[8:9]
	ds_bpermute_b32 v36, v27, v31
	v_lshl_add_u64 v[34:35], v[18:19], 0, s[14:15]
	global_store_dword v[34:35], v17, off offset:256
	s_waitcnt lgkmcnt(0)
	v_add_f32_e32 v17, v31, v36
	v_cndmask_b32_e64 v17, v17, v31, s[10:11]
	global_store_dword v[34:35], v17, off
	v_mov_b32_e32 v20, v116
	s_nop 0
	v_mov_b32_e32 v22, v117
	s_nop 0
	v_mov_b32_e32 v21, v118
	v_mov_b32_e32 v23, v119
	v_mov_b32_e32 v17, v121
	s_waitcnt vmcnt(1)
	v_pk_add_f32 v[20:21], v[20:21], v[22:23]
	s_nop 0
	v_add_f32_e32 v20, v20, v21
	s_waitcnt vmcnt(0)
	v_add_f32_e32 v17, v17, v20
	v_cmp_nlt_f32_e32 vcc, s40, v17
	s_and_saveexec_b64 s[14:15], vcc
	s_cbranch_execz .LBB0_602
	v_mul_f32_e32 v17, 0x3fb8aa3b, v17
	v_exp_f32_e32 v31, v17
	s_nop 0
	v_add_f32_e32 v17, 1.0, v31
	v_frexp_mant_f32_e32 v23, v17
	v_cvt_f64_f32_e32 v[20:21], v17
	v_add_f32_e32 v22, -1.0, v17
	v_frexp_exp_i32_f64_e32 v20, v[20:21]
	v_cmp_gt_f32_e32 vcc, s41, v23
	v_sub_f32_e32 v24, v22, v17
	v_sub_f32_e32 v22, v31, v22
	v_subbrev_co_u32_e32 v34, vcc, 0, v20, vcc
	v_add_f32_e32 v24, 1.0, v24
	v_sub_u32_e32 v20, 0, v34
	v_add_f32_e32 v22, v22, v24
	v_ldexp_f32 v17, v17, v20
	v_ldexp_f32 v20, v22, v20
	v_add_f32_e32 v22, -1.0, v17
	v_add_f32_e32 v21, 1.0, v22
	v_sub_f32_e32 v21, v17, v21
	v_add_f32_e32 v23, v20, v21
	v_add_f32_e32 v21, 1.0, v17
	v_add_f32_e32 v24, -1.0, v21
	v_sub_f32_e32 v17, v17, v24
	v_add_f32_e32 v17, v20, v17
	v_add_f32_e32 v35, v21, v17
	v_rcp_f32_e32 v36, v35
	v_sub_f32_e32 v20, v35, v21
	v_add_f32_e32 v21, v22, v23
	v_sub_f32_e32 v17, v17, v20
	v_mul_f32_e32 v38, v21, v36
	v_sub_f32_e32 v20, v21, v22
	v_mul_f32_e32 v22, v35, v38
	v_fma_f32 v24, v38, v35, -v22
	v_fmac_f32_e32 v24, v38, v17
	v_sub_f32_e32 v37, v23, v20
	v_add_f32_e32 v20, v22, v24
	v_sub_f32_e32 v23, v21, v20
	v_pk_add_f32 v[32:33], v[20:21], v[22:23] neg_lo:[0,1] neg_hi:[0,1]
	v_mov_b32_e32 v25, v20
	v_pk_add_f32 v[20:21], v[32:33], v[24:25] neg_lo:[0,1] neg_hi:[0,1]
	v_cmp_neq_f32_e32 vcc, s63, v31
	v_add_f32_e32 v21, v37, v21
	v_add_f32_e32 v20, v20, v21
	v_add_f32_e32 v21, v23, v20
	v_mul_f32_e32 v37, v36, v21
	v_mul_f32_e32 v22, v35, v37
	v_fma_f32 v24, v37, v35, -v22
	v_fmac_f32_e32 v24, v37, v17
	v_sub_f32_e32 v17, v23, v21
	v_add_f32_e32 v17, v20, v17
	v_add_f32_e32 v20, v22, v24
	v_sub_f32_e32 v23, v21, v20
	v_pk_add_f32 v[32:33], v[20:21], v[22:23] neg_lo:[0,1] neg_hi:[0,1]
	v_mov_b32_e32 v25, v20
	v_pk_add_f32 v[20:21], v[32:33], v[24:25] neg_lo:[0,1] neg_hi:[0,1]
	s_nop 0
	v_add_f32_e32 v17, v17, v21
	v_add_f32_e32 v17, v20, v17
	v_add_f32_e32 v21, v38, v37
	v_add_f32_e32 v17, v23, v17
	v_sub_f32_e32 v20, v21, v38
	v_mul_f32_e32 v17, v36, v17
	v_sub_f32_e32 v20, v37, v20
	v_add_f32_e32 v22, v20, v17
	v_add_f32_e32 v24, v21, v22
	v_cvt_f32_i32_e32 v20, v34
	v_mul_f32_e32 v25, v24, v24
	v_sub_f32_e32 v21, v24, v21
	v_fmamk_f32 v17, v25, 0x3e9b6dac, v59
	v_sub_f32_e32 v21, v22, v21
	v_fmaak_f32 v17, v25, v17, 0x3f2aaada
	v_ldexp_f32 v32, v21, 1
	v_mul_f32_e32 v21, v24, v25
	v_ldexp_f32 v23, v24, 1
	v_pk_mul_f32 v[24:25], v[20:21], v[16:17]
	s_nop 0
	v_fma_f32 v22, v20, s62, -v24
	v_fmac_f32_e32 v22, 0xb102e308, v20
	v_pk_add_f32 v[20:21], v[24:25], v[22:23]
	s_nop 0
	v_sub_f32_e32 v17, v21, v23
	v_sub_f32_e32 v17, v25, v17
	v_add_f32_e32 v33, v32, v17
	v_mov_b32_e32 v32, v24
	v_pk_add_f32 v[24:25], v[20:21], v[24:25] neg_lo:[0,1] neg_hi:[0,1]
	v_pk_add_f32 v[34:35], v[20:21], v[32:33]
	v_mov_b32_e32 v23, v20
	v_mov_b32_e32 v25, v35
	v_pk_add_f32 v[36:37], v[22:23], v[24:25] neg_lo:[0,1] neg_hi:[0,1]
	v_pk_add_f32 v[22:23], v[22:23], v[24:25]
	v_mov_b32_e32 v32, v33
	v_pk_add_f32 v[24:25], v[22:23], v[20:21] op_sel:[1,0] op_sel_hi:[0,1] neg_lo:[0,1] neg_hi:[0,1]
	v_pk_add_f32 v[38:39], v[34:35], v[24:25] op_sel_hi:[1,0] neg_lo:[0,1] neg_hi:[0,1]
	v_mov_b32_e32 v34, v35
	v_mov_b32_e32 v35, v23
	v_pk_mov_b32 v[24:25], v[20:21], v[24:25] op_sel:[1,0]
	v_mov_b32_e32 v33, v20
	v_pk_add_f32 v[24:25], v[34:35], v[24:25] neg_lo:[0,1] neg_hi:[0,1]
	v_mov_b32_e32 v38, v36
	v_pk_add_f32 v[20:21], v[32:33], v[24:25] neg_lo:[0,1] neg_hi:[0,1]
	v_mov_b32_e32 v37, v23
	v_pk_add_f32 v[24:25], v[38:39], v[20:21]
	s_nop 0
	v_pk_add_f32 v[32:33], v[24:25], v[24:25] op_sel:[0,1] op_sel_hi:[1,0]
	s_nop 0
	v_pk_add_f32 v[22:23], v[22:23], v[32:33] op_sel:[1,0] op_sel_hi:[0,1]
	v_mov_b32_e32 v25, v22
	v_pk_add_f32 v[34:35], v[24:25], v[36:37] neg_lo:[0,1] neg_hi:[0,1]
	v_mov_b32_e32 v21, v32
	v_sub_f32_e32 v17, v24, v34
	v_pk_add_f32 v[20:21], v[20:21], v[34:35] neg_lo:[0,1] neg_hi:[0,1]
	v_sub_f32_e32 v17, v36, v17
	v_add_f32_e32 v17, v20, v17
	v_add_f32_e32 v17, v17, v21
	v_add_f32_e32 v17, v22, v17
	v_cndmask_b32_e32 v17, v61, v17, vcc
	v_cmp_ngt_f32_e32 vcc, -1.0, v31
	s_nop 1
	v_cndmask_b32_e32 v17, v62, v17, vcc
	v_cmp_neq_f32_e32 vcc, -1.0, v31
	s_nop 1
	v_cndmask_b32_e32 v17, v63, v17, vcc
	v_cmp_lt_f32_e64 vcc, |v31|, s64
	s_nop 1
	v_cndmask_b32_e32 v17, v17, v31, vcc
	s_branch .LBB0_602
